# NA K/V tile prefetch two tiles ahead: two alternating register sets (tile parity), LDS double buffer unchanged; tile 1 loaded in the item prologue
# speedup vs baseline: 1.0009x; 1.0009x over previous
.LBB0_333:
	v_lshl_add_u32 v0, s34, 9, v115
	s_waitcnt lgkmcnt(0)
	v_mov_b32_e32 v12, v163
	v_ashrrev_i32_e32 v0, 9, v0
	v_bfe_u32 v5, v12, 7, 1
	s_movk_i32 s2, 0x1100
	v_or_b32_e32 v8, v5, v127
	v_mad_i32_i24 v139, v0, s2, v188
	v_lshrrev_b32_e32 v2, 1, v12
	v_and_b32_e32 v138, 15, v12
	v_bfe_u32 v7, v12, 4, 2
	v_mul_i32_i24_e32 v4, 0x1100, v0
	v_lshl_add_u32 v0, v8, 6, v139
	v_and_b32_e32 v6, 32, v2
	v_or3_b32 v122, v0, v6, v138
	v_lshlrev_b32_e32 v0, 4, v7
	v_lshl_add_u64 v[2:3], v[116:117], 0, v[0:1]
	s_movk_i32 s4, 0x1800
	v_or_b32_e32 v120, 16, v122
	v_bfe_u32 v141, v12, 3, 5
	v_mad_i64_i32 v[10:11], s[2:3], v122, s4, v[2:3]
	v_mad_i64_i32 v[2:3], s[2:3], v120, s4, v[2:3]
	v_add_u32_e32 v18, v139, v129
	v_or_b32_e32 v143, 32, v141
	v_and_b32_e32 v28, 0xff, v12
	global_load_dwordx4 v[38:41], v[10:11], off
	global_load_dwordx4 v[34:37], v[10:11], off offset:64
	global_load_dwordx4 v[46:49], v[2:3], off
	global_load_dwordx4 v[42:45], v[2:3], off offset:64
	v_readlane_b32 s6, v252, 60
	v_readlane_b32 s7, v252, 61
	v_add_lshl_u32 v50, v130, v28, 2
	v_mov_b32_e32 v51, 0
	v_cmp_ge_u32_e32 vcc, s12, v28
	v_lshl_add_u64 v[50:51], s[6:7], 0, v[50:51]
	global_load_dword v52, v[50:51], off
	s_and_saveexec_b64 s[6:7], vcc
	global_load_dword v53, v[50:51], off offset:1024
	s_mov_b64 exec, s[6:7]
	v_or_b32_e32 v0, v141, v18
	v_mov_b64_e32 v[2:3], s[26:27]
	v_lshlrev_b32_e32 v12, 3, v12
	v_or_b32_e32 v18, v143, v18
	v_mad_i64_i32 v[10:11], s[2:3], v0, s4, v[2:3]
	v_lshlrev_b32_e32 v0, 1, v114
	v_and_b32_e32 v124, 56, v12
	v_mad_i64_i32 v[2:3], s[2:3], v18, s4, v[2:3]
	v_lshl_add_u64 v[10:11], v[10:11], 0, v[0:1]
	v_lshlrev_b32_e32 v26, 1, v124
	v_mov_b32_e32 v27, v1
	v_lshl_add_u64 v[2:3], v[2:3], 0, v[0:1]
	v_lshl_add_u64 v[14:15], v[10:11], 0, v[26:27]
	s_movk_i32 s5, 0x1000
	v_lshl_add_u64 v[2:3], v[2:3], 0, v[26:27]
	global_load_dwordx4 v[10:13], v[14:15], off offset:2048
	global_load_dwordx4 v[18:21], v[2:3], off offset:2048
	v_add_co_u32_e32 v14, vcc, s5, v14
	v_readlane_b32 s2, v252, 60
	s_nop 0
	v_addc_co_u32_e32 v15, vcc, 0, v15, vcc
	global_load_dwordx4 v[14:17], v[14:15], off
	v_add_co_u32_e32 v2, vcc, s5, v2
	v_readlane_b32 s3, v252, 61
	s_nop 0
	v_addc_co_u32_e32 v3, vcc, 0, v3, vcc
	global_load_dwordx4 v[22:25], v[2:3], off
	v_mul_u32_u24_e32 v2, 0x48, v141
	v_lshlrev_b32_e32 v2, 1, v2
	v_add3_u32 v2, v222, v2, v26
	v_mov_b32_e32 v3, v1
	v_lshlrev_b32_e32 v9, 3, v7
	v_ashrrev_i32_e32 v123, 31, v122
	v_ashrrev_i32_e32 v121, 31, v120
	s_mov_b64 s[4:5], 0
	s_waitcnt vmcnt(3)
	ds_write_b128 v2, v[10:13]
	s_waitcnt vmcnt(1)
	ds_write_b128 v2, v[14:17] offset:18432
	ds_write_b128 v2, v[18:21] offset:4608
	s_waitcnt vmcnt(0)
	ds_write_b128 v2, v[22:25] offset:23040
	v_lshlrev_b32_e32 v10, 2, v28
	v_add_u32_e32 v11, v131, v10
	v_mul_f32_e32 v52, 0x3fb8aa3b, v52
	v_cmp_ge_u32_e32 vcc, s12, v28
	ds_write_b32 v11, v52
	s_and_saveexec_b64 s[4:5], vcc
	v_mul_f32_e32 v53, 0x3fb8aa3b, v53
	ds_write_b32 v11, v53 offset:1024
	s_or_b64 exec, exec, s[4:5]
	v_lshlrev_b32_e32 v134, 2, v7
	v_lshrrev_b32_e32 v7, 2, v138
	v_or_b32_e32 v3, v6, v138
	v_or_b32_e32 v135, v134, v7
	v_and_b32_e32 v7, 12, v10
	v_lshl_add_u32 v136, v7, 1, v222
	v_sub_u32_e64 v7, v3, 8 clamp
	v_sub_u32_e32 v7, v134, v7
	v_sub_u32_e64 v2, v8, 4 clamp
	v_add_u32_e32 v8, 1, v7
	v_cmp_gt_u32_e64 s[42:43], 16, v8
	v_add_u32_e32 v8, 2, v7
	v_cmp_gt_u32_e64 s[44:45], 16, v8
	v_add_u32_e32 v8, 3, v7
	v_cmp_gt_u32_e64 s[46:47], 16, v8
	v_add_u32_e32 v8, 17, v7
	v_cmp_gt_u32_e64 s[50:51], 16, v8
	v_add_u32_e32 v8, 18, v7
	v_cmp_gt_u32_e64 s[52:53], 16, v8
	v_add_u32_e32 v8, 19, v7
	v_cmp_gt_u32_e64 s[54:55], 16, v8
	v_and_b32_e32 v8, -16, v7
	s_movk_i32 s3, 0xffe0
	s_movk_i32 s6, 0xffd0
	v_cmp_eq_u32_e64 s[56:57], s3, v8
	v_cmp_eq_u32_e64 s[64:65], s6, v8
	v_add_u32_e32 v8, 49, v7
	v_min_u32_e32 v3, 40, v3
	v_cmp_gt_u32_e64 s[66:67], 16, v8
	v_add_u32_e32 v8, 50, v7
	v_sub_u32_e32 v3, v134, v3
	v_cmp_gt_u32_e64 s[68:69], 16, v8
	v_add_u32_e32 v8, -7, v3
	v_cmp_gt_u32_e64 s[74:75], 16, v8
	v_add_u32_e32 v8, -6, v3
	v_lshl_add_u32 v145, v9, 1, v222
	v_add_u32_e32 v9, 33, v7
	v_cmp_gt_u32_e64 s[76:77], 16, v8
	v_add_u32_e32 v8, -5, v3
	s_movk_i32 s2, 0xffef
	v_cmp_gt_u32_e64 s[58:59], 16, v9
	v_add_u32_e32 v9, 34, v7
	v_cmp_gt_u32_e64 s[78:79], 16, v8
	v_add_u32_e32 v8, 9, v3
	v_cmp_gt_u32_e64 s[40:41], 16, v7
	v_cmp_lt_u32_e64 s[48:49], s2, v7
	v_cmp_gt_u32_e64 s[60:61], 16, v9
	v_add_u32_e32 v9, 35, v7
	v_add_u32_e32 v7, 51, v7
	v_cmp_gt_u32_e64 s[82:83], 16, v8
	v_add_u32_e32 v8, 10, v3
	v_cmp_gt_u32_e64 s[70:71], 16, v7
	v_add_u32_e32 v7, -8, v3
	v_cmp_gt_u32_e64 s[84:85], 16, v8
	v_add_u32_e32 v8, 11, v3
	v_cmp_gt_u32_e64 s[72:73], 16, v7
	v_cmp_lt_u32_e64 s[80:81], s2, v7
	v_cmp_gt_u32_e64 s[86:87], 16, v8
	v_and_b32_e32 v7, -16, v7
	v_add_u32_e32 v8, 25, v3
	v_cmp_eq_u32_e64 s[88:89], s3, v7
	v_cmp_gt_u32_e64 s[90:91], 16, v8
	v_add_u32_e32 v8, 26, v3
	v_cmp_eq_u32_e64 s[94:95], s6, v7
	v_add_u32_e32 v7, 41, v3
	v_cmp_gt_u32_e64 s[92:93], 16, v8
	v_add_u32_e32 v8, 27, v3
	v_cmp_gt_u32_e64 s[6:7], 16, v7
	v_add_u32_e32 v7, 42, v3
	v_add_u32_e32 v3, 43, v3
	v_cmp_gt_u32_e64 s[96:97], 16, v3
	v_sub_u32_e32 v3, v132, v5
	v_sub_u32_e32 v5, v134, v138
	v_sub_u32_e32 v5, v5, v6
	v_min_u32_e32 v2, 56, v2
	v_mul_i32_i24_e32 v3, 0x7c, v3
	v_lshlrev_b32_e32 v5, 2, v5
	v_mov_b32_e32 v18, v1
	v_mov_b32_e32 v19, v1
	v_mov_b32_e32 v20, v1
	v_mov_b32_e32 v21, v1
	v_cmp_gt_u32_e64 s[62:63], 16, v9
	v_cmp_gt_u32_e64 s[4:5], 16, v8
	v_cmp_gt_u32_e64 s[8:9], 16, v7
	v_add3_u32 v147, v3, v5, v126
	v_sub_u32_e32 v148, v128, v2
	v_add_u32_e32 v149, 0xfffffe00, v4
	v_mov_b64_e32 v[32:33], v[20:21]
	v_mov_b64_e32 v[24:25], v[20:21]
	v_mov_b64_e32 v[28:29], v[20:21]
	v_mov_b64_e32 v[10:11], v[18:19]
	v_mov_b64_e32 v[14:15], v[18:19]
	v_mov_b64_e32 v[2:3], v[18:19]
	v_mov_b64_e32 v[6:7], v[18:19]
	v_lshl_add_u32 v146, v124, 1, v222
	s_mov_b32 s14, 0
	v_mov_b32_e32 v144, 0xf149f2ca
	v_mov_b32_e32 v140, 0
	v_mov_b64_e32 v[30:31], v[18:19]
	v_mov_b64_e32 v[22:23], v[18:19]
	v_mov_b64_e32 v[26:27], v[18:19]
	v_mov_b64_e32 v[12:13], v[20:21]
	v_mov_b64_e32 v[16:17], v[20:21]
	v_mov_b64_e32 v[4:5], v[20:21]
	v_mov_b64_e32 v[8:9], v[20:21]
	v_mov_b32_e32 v137, 0
	v_mov_b32_e32 v142, 0xf149f2ca
	s_mov_b32 s24, 0
	v_min_i32_e32 v66, 63, v133
	v_lshl_add_u32 v66, v66, 6, v139
	v_add_u32_e32 v68, v66, v141
	v_mov_b64_e32 v[70:71], s[26:27]
	s_movk_i32 s10, 0x1800
	v_mad_i64_i32 v[68:69], s[2:3], v68, s10, v[70:71]
	v_lshl_add_u64 v[68:69], v[68:69], 0, v[0:1]
	v_lshlrev_b32_e32 v72, 1, v124
	v_add_u32_e32 v72, 0x800, v72
	v_mov_b32_e32 v73, v1
	v_add_u32_e32 v66, v66, v143
	v_lshl_add_u64 v[68:69], v[68:69], 0, v[72:73]
	v_mad_i64_i32 v[66:67], s[2:3], v66, s10, v[70:71]
	v_lshl_add_u64 v[66:67], v[66:67], 0, v[0:1]
	v_lshl_add_u64 v[66:67], v[66:67], 0, v[72:73]
	global_load_dwordx4 v[50:53], v[68:69], off
	global_load_dwordx4 v[54:57], v[68:69], off offset:2048
	global_load_dwordx4 v[58:61], v[66:67], off
	global_load_dwordx4 v[62:65], v[66:67], off offset:2048
	v_and_b32_e32 v66, 15, v163
	v_lshrrev_b32_e32 v67, 2, v163
	v_and_b32_e32 v67, 12, v67
	v_lshrrev_b32_e32 v68, 1, v163
	v_and_b32_e32 v68, 32, v68
	v_add_u32_e32 v66, v68, v66
	v_lshrrev_b32_e32 v69, 2, v68
	v_sub_u32_e32 v68, v68, v69
	v_sub_u32_e64 v69, v66, 8 clamp
	v_min_u32_e32 v69, 48, v69
	v_add_u32_e32 v70, 8, v66
	v_min_u32_e32 v70, 48, v70
	v_sub_u32_e32 v69, v67, v69
	v_add_u32_e32 v69, v69, v68
	v_sub_u32_e32 v70, v67, v70
	v_add3_u32 v70, v70, v68, 8
	v_add_u32_e32 v71, 0, v69
	v_cmp_gt_u32_e64 s[40:41], 16, v71
	v_add_u32_e32 v71, 1, v69
	v_cmp_gt_u32_e64 s[42:43], 16, v71
	v_add_u32_e32 v71, 2, v69
	v_cmp_gt_u32_e64 s[44:45], 16, v71
	v_add_u32_e32 v71, 3, v69
	v_cmp_gt_u32_e64 s[46:47], 16, v71
	v_add_u32_e32 v71, 16, v69
	v_cmp_gt_u32_e64 s[48:49], 16, v71
	v_add_u32_e32 v71, 17, v69
	v_cmp_gt_u32_e64 s[50:51], 16, v71
	v_add_u32_e32 v71, 18, v69
	v_cmp_gt_u32_e64 s[52:53], 16, v71
	v_add_u32_e32 v71, 19, v69
	v_cmp_gt_u32_e64 s[54:55], 16, v71
	v_add_u32_e32 v71, 0, v70
	v_cmp_gt_u32_e64 s[72:73], 16, v71
	v_add_u32_e32 v71, 1, v70
	v_cmp_gt_u32_e64 s[74:75], 16, v71
	v_add_u32_e32 v71, 2, v70
	v_cmp_gt_u32_e64 s[76:77], 16, v71
	v_add_u32_e32 v71, 3, v70
	v_cmp_gt_u32_e64 s[78:79], 16, v71
	v_add_u32_e32 v71, 16, v70
	v_cmp_gt_u32_e64 s[80:81], 16, v71
	v_add_u32_e32 v71, 17, v70
	v_cmp_gt_u32_e64 s[82:83], 16, v71
	v_add_u32_e32 v71, 18, v70
	v_cmp_gt_u32_e64 s[84:85], 16, v71
	v_add_u32_e32 v71, 19, v70
	v_cmp_gt_u32_e64 s[86:87], 16, v71
	s_waitcnt lgkmcnt(0)
	s_barrier
	s_branch .LBB0_338

.LBB0_337:
	s_or_b64 exec, exec, s[38:39]
	v_bitop3_b32 v66, s15, v141, 64 bitop3:0xde
	v_mul_u32_u24_e32 v66, 0x48, v66
	v_lshl_add_u32 v66, v66, 1, v146
	v_bitop3_b32 v67, s15, v143, 64 bitop3:0xde
	v_mul_u32_u24_e32 v67, 0x48, v67
	v_lshl_add_u32 v67, v67, 1, v146
	v_add_u32_e32 v147, 0x7c, v147
	s_cmp_eq_u32 s24, 11
	s_cbranch_scc1 .Lna_st_last
	s_bitcmp1_b32 s24, 0
	s_cbranch_scc1 .Lna_st_B
	s_waitcnt vmcnt(7)
	ds_write_b128 v66, v[50:53]
	s_waitcnt vmcnt(6)
	ds_write_b128 v66, v[54:57] offset:18432
	s_waitcnt vmcnt(5)
	ds_write_b128 v67, v[58:61]
	s_waitcnt vmcnt(4)
	ds_write_b128 v67, v[62:65] offset:18432
	s_branch .Lna_st_done
.Lna_st_B:
	s_waitcnt vmcnt(7)
	ds_write_b128 v66, v[224:227]
	s_waitcnt vmcnt(6)
	ds_write_b128 v66, v[228:231] offset:18432
	s_waitcnt vmcnt(5)
	ds_write_b128 v67, v[232:235]
	s_waitcnt vmcnt(4)
	ds_write_b128 v67, v[236:239] offset:18432
	s_branch .Lna_st_done
.Lna_st_last:
	s_waitcnt vmcnt(3)
	ds_write_b128 v66, v[224:227]
	s_waitcnt vmcnt(2)
	ds_write_b128 v66, v[228:231] offset:18432
	s_waitcnt vmcnt(1)
	ds_write_b128 v67, v[232:235]
	s_waitcnt vmcnt(0)
	ds_write_b128 v67, v[236:239] offset:18432
.Lna_st_done:
	s_add_i32 s24, s24, 1
	s_add_i32 s14, s14, 64
	s_cmp_lg_u32 s24, 12
	s_waitcnt lgkmcnt(0)
	s_barrier
	s_cbranch_scc0 .LBB0_419
.LBB0_338:
	s_cmp_gt_u32 s24, 10
	s_cbranch_scc1 .Lna_pf_done
	s_cmp_gt_u32 s24, 6
	s_cbranch_scc1 .Lna_pf_ctx
	v_add3_u32 v66, s24, v133, 1
	v_min_i32_e32 v66, 63, v66
	v_lshl_add_u32 v66, v66, 6, v139
	s_branch .Lna_pf_addr
.Lna_pf_ctx:
	v_add3_u32 v66, s14, v149, 64
.Lna_pf_addr:
	v_add_u32_e32 v68, v66, v141
	v_mov_b64_e32 v[70:71], s[26:27]
	s_movk_i32 s10, 0x1800
	v_mad_i64_i32 v[68:69], s[2:3], v68, s10, v[70:71]
	v_lshl_add_u64 v[68:69], v[68:69], 0, v[0:1]
	v_lshlrev_b32_e32 v72, 1, v124
	v_add_u32_e32 v72, 0x800, v72
	v_mov_b32_e32 v73, v1
	v_add_u32_e32 v66, v66, v143
	v_lshl_add_u64 v[68:69], v[68:69], 0, v[72:73]
	v_mad_i64_i32 v[66:67], s[2:3], v66, s10, v[70:71]
	v_lshl_add_u64 v[66:67], v[66:67], 0, v[0:1]
	v_lshl_add_u64 v[66:67], v[66:67], 0, v[72:73]
	s_bitcmp1_b32 s24, 0
	s_cbranch_scc1 .Lna_pf_setA
	global_load_dwordx4 v[224:227], v[68:69], off
	global_load_dwordx4 v[228:231], v[68:69], off offset:2048
	global_load_dwordx4 v[232:235], v[66:67], off
	global_load_dwordx4 v[236:239], v[66:67], off offset:2048
	s_branch .Lna_pf_done
.Lna_pf_setA:
	global_load_dwordx4 v[50:53], v[68:69], off
	global_load_dwordx4 v[54:57], v[68:69], off offset:2048
	global_load_dwordx4 v[58:61], v[66:67], off
	global_load_dwordx4 v[62:65], v[66:67], off offset:2048
.Lna_pf_done:
	s_and_b32 s15, s14, 64
	v_add_u32_e32 v66, s24, v148
	s_cmp_gt_u32 s24, 8
	s_cselect_b64 s[10:11], -1, 0
	s_cmp_lt_u32 s24, 9
	v_cmp_gt_u32_e32 vcc, 8, v66
	s_movk_i32 s13, 0x1800
	s_cselect_b64 s[28:29], -1, 0
	s_or_b64 s[2:3], s[10:11], vcc
	s_and_saveexec_b64 s[38:39], s[2:3]
	s_cbranch_execz .LBB0_337
	v_or_b32_e32 v66, s15, v138
	v_mad_u32_u24 v82, v66, s16, v145
	s_cmp_lt_u32 s24, 9
	s_cbranch_scc0 .Lna_ctx_tile
	s_bitcmp1_b32 s100, 6
	s_cbranch_scc1 .Lna_loc_h1
	ds_read_b128 v[164:167], v82 offset:0
	ds_read_b128 v[168:171], v82 offset:64
	ds_read_b128 v[172:175], v82 offset:2304
	ds_read_b128 v[176:179], v82 offset:2368
	ds_read2_b32 v[70:71], v147 offset0:16 offset1:17
	ds_read2_b32 v[72:73], v147 offset0:18 offset1:19
	ds_read2_b32 v[78:79], v147 offset0:32 offset1:33
	ds_read2_b32 v[80:81], v147 offset0:34 offset1:35
	ds_read_b128 v[180:183], v82 offset:1152
	ds_read_b128 v[184:187], v82 offset:1216
	ds_read_b128 v[154:157], v82 offset:3456
	ds_read_b128 v[200:203], v82 offset:3520
	v_mov_b32_e32 v158, 0xf149f2ca
	s_waitcnt lgkmcnt(11)
	v_mfma_f32_16x16x32_bf16 v[90:93], v[164:167], v[38:41], 0
	s_waitcnt lgkmcnt(9)
	v_mfma_f32_16x16x32_bf16 v[94:97], v[172:175], v[38:41], 0
	v_mfma_f32_16x16x32_bf16 v[90:93], v[168:171], v[34:37], v[90:93]
	s_waitcnt lgkmcnt(8)
	v_mfma_f32_16x16x32_bf16 v[94:97], v[176:179], v[34:37], v[94:97]
	ds_read2_b32 v[84:85], v147 offset0:8 offset1:9
	ds_read2_b32 v[86:87], v147 offset0:10 offset1:11
	ds_read2_b32 v[106:107], v147 offset0:24 offset1:25
	ds_read2_b32 v[108:109], v147 offset0:26 offset1:27
	s_waitcnt lgkmcnt(7)
	v_mfma_f32_16x16x32_bf16 v[98:101], v[180:183], v[46:49], 0
	v_or_b32_e32 v160, s15, v135
	v_mul_u32_u24_e32 v160, 0x48, v160
	v_lshl_add_u32 v160, v160, 1, v136
	v_fmac_f32_e32 v70, 0x3e38aa3b, v90
	v_fmac_f32_e32 v71, 0x3e38aa3b, v91
	v_fmac_f32_e32 v72, 0x3e38aa3b, v92
	s_waitcnt lgkmcnt(5)
	v_mfma_f32_16x16x32_bf16 v[102:105], v[154:157], v[46:49], 0
	v_fmac_f32_e32 v73, 0x3e38aa3b, v93
	v_fmac_f32_e32 v78, 0x3e38aa3b, v94
	v_fmac_f32_e32 v79, 0x3e38aa3b, v95
	v_fmac_f32_e32 v80, 0x3e38aa3b, v96
	v_fmac_f32_e32 v81, 0x3e38aa3b, v97
	v_cndmask_b32_e64 v70, v158, v70, s[40:41]
	v_mfma_f32_16x16x32_bf16 v[98:101], v[184:187], v[42:45], v[98:101]
	v_cndmask_b32_e64 v71, v158, v71, s[42:43]
	v_cndmask_b32_e64 v72, v158, v72, s[44:45]
	v_cndmask_b32_e64 v73, v158, v73, s[46:47]
	v_cndmask_b32_e64 v78, v158, v78, s[48:49]
	v_cndmask_b32_e64 v79, v158, v79, s[50:51]
	v_cndmask_b32_e64 v80, v158, v80, s[52:53]
	s_waitcnt lgkmcnt(4)
	v_mfma_f32_16x16x32_bf16 v[102:105], v[200:203], v[42:45], v[102:105]
	v_cndmask_b32_e64 v81, v158, v81, s[54:55]
	v_max3_f32 v150, v70, s18, v71
	v_max3_f32 v150, v150, v72, v73
	v_max3_f32 v150, v150, v78, v79
	v_max3_f32 v150, v150, v80, v81
	s_waitcnt lgkmcnt(0)
	ds_read_b64_tr_b16 v[164:165], v160 offset:18432
	ds_read_b64_tr_b16 v[166:167], v160 offset:20736
	ds_read_b64_tr_b16 v[168:169], v160 offset:18464
	ds_read_b64_tr_b16 v[170:171], v160 offset:20768
	ds_read_b64_tr_b16 v[172:173], v160 offset:18496
	ds_read_b64_tr_b16 v[174:175], v160 offset:20800
	ds_read_b64_tr_b16 v[176:177], v160 offset:18528
	ds_read_b64_tr_b16 v[178:179], v160 offset:20832
	v_fmac_f32_e32 v84, 0x3e38aa3b, v98
	v_fmac_f32_e32 v85, 0x3e38aa3b, v99
	v_fmac_f32_e32 v86, 0x3e38aa3b, v100
	v_fmac_f32_e32 v87, 0x3e38aa3b, v101
	v_fmac_f32_e32 v106, 0x3e38aa3b, v102
	v_fmac_f32_e32 v107, 0x3e38aa3b, v103
	v_fmac_f32_e32 v108, 0x3e38aa3b, v104
	v_fmac_f32_e32 v109, 0x3e38aa3b, v105
	v_cndmask_b32_e64 v84, v158, v84, s[72:73]
	v_cndmask_b32_e64 v85, v158, v85, s[74:75]
	v_cndmask_b32_e64 v86, v158, v86, s[76:77]
	v_cndmask_b32_e64 v87, v158, v87, s[78:79]
	v_cndmask_b32_e64 v106, v158, v106, s[80:81]
	v_cndmask_b32_e64 v107, v158, v107, s[82:83]
	v_cndmask_b32_e64 v108, v158, v108, s[84:85]
	v_cndmask_b32_e64 v109, v158, v109, s[86:87]
	v_max3_f32 v151, v84, s18, v85
	v_max3_f32 v151, v151, v86, v87
	v_max3_f32 v151, v151, v106, v107
	v_max3_f32 v151, v151, v108, v109
	v_mov_b32_e32 v152, v150
	v_mov_b32_e32 v153, v151
	s_nop 0
	v_permlane16_swap_b32_e32 v152, v150
	v_permlane16_swap_b32_e32 v153, v151
	v_max_f32_e32 v150, v150, v152
	v_max_f32_e32 v151, v151, v153
	v_mov_b32_e32 v152, v150
	v_mov_b32_e32 v153, v151
	s_nop 0
	v_permlane32_swap_b32_e32 v152, v150
	v_permlane32_swap_b32_e32 v153, v151
	v_max_f32_e32 v150, v150, v152
	v_max_f32_e32 v151, v151, v153
	v_add_f32_e32 v110, 0x41000000, v144
	v_cmp_gt_f32_e32 vcc, v150, v110
	s_cbranch_vccz .Lna_l0_keep0
	v_max_f32_e32 v244, v144, v150
	v_sub_f32_e32 v110, v144, v244
	v_exp_f32_e32 v110, v110
	v_mov_b32_e32 v144, v244
	v_mul_f32_e32 v140, v140, v110
	v_pk_mul_f32 v[18:19], v[18:19], v[110:111] op_sel_hi:[1,0]
	v_pk_mul_f32 v[20:21], v[20:21], v[110:111] op_sel_hi:[1,0]
	v_pk_mul_f32 v[22:23], v[22:23], v[110:111] op_sel_hi:[1,0]
	v_pk_mul_f32 v[24:25], v[24:25], v[110:111] op_sel_hi:[1,0]
	v_pk_mul_f32 v[10:11], v[10:11], v[110:111] op_sel_hi:[1,0]
	v_pk_mul_f32 v[12:13], v[12:13], v[110:111] op_sel_hi:[1,0]
	v_pk_mul_f32 v[2:3], v[2:3], v[110:111] op_sel_hi:[1,0]
	v_pk_mul_f32 v[4:5], v[4:5], v[110:111] op_sel_hi:[1,0]

.Lna_l0_keep1:
	s_waitcnt lgkmcnt(6)
	ds_read_b64_tr_b16 v[180:181], v160 offset:19584
	ds_read_b64_tr_b16 v[182:183], v160 offset:21888
	ds_read_b64_tr_b16 v[184:185], v160 offset:19616
	ds_read_b64_tr_b16 v[186:187], v160 offset:21920
	ds_read_b64_tr_b16 v[154:155], v160 offset:19648
	ds_read_b64_tr_b16 v[156:157], v160 offset:21952
	ds_read_b64_tr_b16 v[200:201], v160 offset:19680
	ds_read_b64_tr_b16 v[202:203], v160 offset:21984
	v_sub_f32_e32 v70, v70, v144
	v_sub_f32_e32 v71, v71, v144
	v_exp_f32_e32 v70, v70
	v_sub_f32_e32 v72, v72, v144
	v_exp_f32_e32 v71, v71
	v_sub_f32_e32 v73, v73, v144
	v_exp_f32_e32 v72, v72
	v_exp_f32_e32 v73, v73
	v_sub_f32_e32 v78, v78, v144
	v_sub_f32_e32 v79, v79, v144
	v_exp_f32_e32 v78, v78
	v_sub_f32_e32 v80, v80, v144
	v_exp_f32_e32 v79, v79
	v_sub_f32_e32 v81, v81, v144
	v_exp_f32_e32 v80, v80
	v_exp_f32_e32 v81, v81
	v_add_f32_e32 v246, 0, v70
	v_add_f32_e32 v246, v71, v246
	v_add_f32_e32 v246, v72, v246
	v_add_f32_e32 v246, v73, v246
	v_cvt_pk_bf16_f32 v66, v70, v71
	v_cvt_pk_bf16_f32 v67, v72, v73
	v_add_f32_e32 v246, v78, v246
	v_add_f32_e32 v246, v79, v246
	v_add_f32_e32 v246, v80, v246
	v_add_f32_e32 v246, v81, v246
	v_cvt_pk_bf16_f32 v68, v78, v79
	v_cvt_pk_bf16_f32 v69, v80, v81
	v_add_f32_e32 v140, v140, v246
	s_nop 0
	v_mfma_f32_16x16x32_bf16 v[18:21], v[164:167], v[66:69], v[18:21]
	v_sub_f32_e32 v84, v84, v142
	v_sub_f32_e32 v85, v85, v142
	v_exp_f32_e32 v84, v84
	v_sub_f32_e32 v86, v86, v142
	v_exp_f32_e32 v85, v85
	v_sub_f32_e32 v87, v87, v142
	v_exp_f32_e32 v86, v86
	v_exp_f32_e32 v87, v87
	s_waitcnt lgkmcnt(12)
	v_mfma_f32_16x16x32_bf16 v[22:25], v[168:171], v[66:69], v[22:25]
	v_sub_f32_e32 v106, v106, v142
	v_sub_f32_e32 v107, v107, v142
	v_exp_f32_e32 v106, v106
	v_sub_f32_e32 v108, v108, v142
	v_exp_f32_e32 v107, v107
	v_sub_f32_e32 v109, v109, v142
	v_exp_f32_e32 v108, v108
	v_exp_f32_e32 v109, v109
	s_waitcnt lgkmcnt(10)
	v_mfma_f32_16x16x32_bf16 v[10:13], v[172:175], v[66:69], v[10:13]
	v_add_f32_e32 v247, 0, v84
	v_add_f32_e32 v247, v85, v247
	v_add_f32_e32 v247, v86, v247
	v_add_f32_e32 v247, v87, v247
	v_cvt_pk_bf16_f32 v74, v84, v85
	v_cvt_pk_bf16_f32 v75, v86, v87
	v_add_f32_e32 v247, v106, v247
	v_add_f32_e32 v247, v107, v247
	s_waitcnt lgkmcnt(8)
	v_mfma_f32_16x16x32_bf16 v[2:5], v[176:179], v[66:69], v[2:5]
	v_add_f32_e32 v247, v108, v247
	v_add_f32_e32 v247, v109, v247
	v_cvt_pk_bf16_f32 v76, v106, v107
	v_cvt_pk_bf16_f32 v77, v108, v109
	v_add_f32_e32 v137, v137, v247
	s_waitcnt lgkmcnt(6)
	v_mfma_f32_16x16x32_bf16 v[30:33], v[180:183], v[74:77], v[30:33]
	s_waitcnt lgkmcnt(4)
	v_mfma_f32_16x16x32_bf16 v[26:29], v[184:187], v[74:77], v[26:29]
	s_waitcnt lgkmcnt(2)
	v_mfma_f32_16x16x32_bf16 v[14:17], v[154:157], v[74:77], v[14:17]
	s_waitcnt lgkmcnt(0)
	v_mfma_f32_16x16x32_bf16 v[6:9], v[200:203], v[74:77], v[6:9]
	s_branch .LBB0_337
.Lna_loc_h1:
	ds_read_b128 v[164:167], v82 offset:3456
	ds_read_b128 v[168:171], v82 offset:3520
	ds_read_b128 v[172:175], v82 offset:5760
	ds_read_b128 v[176:179], v82 offset:5824
	ds_read2_b32 v[70:71], v147 offset0:40 offset1:41
	ds_read2_b32 v[72:73], v147 offset0:42 offset1:43
	ds_read2_b32 v[78:79], v147 offset0:56 offset1:57
	ds_read2_b32 v[80:81], v147 offset0:58 offset1:59
	ds_read_b128 v[180:183], v82 offset:4608
	ds_read_b128 v[184:187], v82 offset:4672
	ds_read_b128 v[154:157], v82 offset:6912
	ds_read_b128 v[200:203], v82 offset:6976
	v_mov_b32_e32 v158, 0xf149f2ca
	s_waitcnt lgkmcnt(11)
	v_mfma_f32_16x16x32_bf16 v[90:93], v[164:167], v[38:41], 0
	s_waitcnt lgkmcnt(9)
	v_mfma_f32_16x16x32_bf16 v[94:97], v[172:175], v[38:41], 0
	v_mfma_f32_16x16x32_bf16 v[90:93], v[168:171], v[34:37], v[90:93]
	s_waitcnt lgkmcnt(8)
	v_mfma_f32_16x16x32_bf16 v[94:97], v[176:179], v[34:37], v[94:97]
	ds_read2_b32 v[84:85], v147 offset0:32 offset1:33
	ds_read2_b32 v[86:87], v147 offset0:34 offset1:35
	ds_read2_b32 v[106:107], v147 offset0:48 offset1:49
	ds_read2_b32 v[108:109], v147 offset0:50 offset1:51
	s_waitcnt lgkmcnt(7)
	v_mfma_f32_16x16x32_bf16 v[98:101], v[180:183], v[46:49], 0
	v_or_b32_e32 v160, s15, v135
	v_mul_u32_u24_e32 v160, 0x48, v160
	v_lshl_add_u32 v160, v160, 1, v136
	v_fmac_f32_e32 v70, 0x3e38aa3b, v90
	v_fmac_f32_e32 v71, 0x3e38aa3b, v91
	v_fmac_f32_e32 v72, 0x3e38aa3b, v92
	s_waitcnt lgkmcnt(5)
	v_mfma_f32_16x16x32_bf16 v[102:105], v[154:157], v[46:49], 0
	v_fmac_f32_e32 v73, 0x3e38aa3b, v93
	v_fmac_f32_e32 v78, 0x3e38aa3b, v94
	v_fmac_f32_e32 v79, 0x3e38aa3b, v95
	v_fmac_f32_e32 v80, 0x3e38aa3b, v96
	v_fmac_f32_e32 v81, 0x3e38aa3b, v97
	v_cndmask_b32_e64 v70, v158, v70, s[40:41]
	v_mfma_f32_16x16x32_bf16 v[98:101], v[184:187], v[42:45], v[98:101]
	v_cndmask_b32_e64 v71, v158, v71, s[42:43]
	v_cndmask_b32_e64 v72, v158, v72, s[44:45]
	v_cndmask_b32_e64 v73, v158, v73, s[46:47]
	v_cndmask_b32_e64 v78, v158, v78, s[48:49]
	v_cndmask_b32_e64 v79, v158, v79, s[50:51]
	v_cndmask_b32_e64 v80, v158, v80, s[52:53]
	s_waitcnt lgkmcnt(4)
	v_mfma_f32_16x16x32_bf16 v[102:105], v[200:203], v[42:45], v[102:105]
	v_cndmask_b32_e64 v81, v158, v81, s[54:55]
	v_max3_f32 v150, v70, s18, v71
	v_max3_f32 v150, v150, v72, v73
	v_max3_f32 v150, v150, v78, v79
	v_max3_f32 v150, v150, v80, v81
	s_waitcnt lgkmcnt(0)
	ds_read_b64_tr_b16 v[164:165], v160 offset:21888
	ds_read_b64_tr_b16 v[166:167], v160 offset:24192
	ds_read_b64_tr_b16 v[168:169], v160 offset:21920
	ds_read_b64_tr_b16 v[170:171], v160 offset:24224
	ds_read_b64_tr_b16 v[172:173], v160 offset:21952
	ds_read_b64_tr_b16 v[174:175], v160 offset:24256
	ds_read_b64_tr_b16 v[176:177], v160 offset:21984
	ds_read_b64_tr_b16 v[178:179], v160 offset:24288
	v_fmac_f32_e32 v84, 0x3e38aa3b, v98
	v_fmac_f32_e32 v85, 0x3e38aa3b, v99
	v_fmac_f32_e32 v86, 0x3e38aa3b, v100
	v_fmac_f32_e32 v87, 0x3e38aa3b, v101
	v_fmac_f32_e32 v106, 0x3e38aa3b, v102
	v_fmac_f32_e32 v107, 0x3e38aa3b, v103
	v_fmac_f32_e32 v108, 0x3e38aa3b, v104
	v_fmac_f32_e32 v109, 0x3e38aa3b, v105
	v_cndmask_b32_e64 v84, v158, v84, s[72:73]
	v_cndmask_b32_e64 v85, v158, v85, s[74:75]
	v_cndmask_b32_e64 v86, v158, v86, s[76:77]
	v_cndmask_b32_e64 v87, v158, v87, s[78:79]
	v_cndmask_b32_e64 v106, v158, v106, s[80:81]
	v_cndmask_b32_e64 v107, v158, v107, s[82:83]
	v_cndmask_b32_e64 v108, v158, v108, s[84:85]
	v_cndmask_b32_e64 v109, v158, v109, s[86:87]
	v_max3_f32 v151, v84, s18, v85
	v_max3_f32 v151, v151, v86, v87
	v_max3_f32 v151, v151, v106, v107
	v_max3_f32 v151, v151, v108, v109
	v_mov_b32_e32 v152, v150
	v_mov_b32_e32 v153, v151
	s_nop 0
	v_permlane16_swap_b32_e32 v152, v150
	v_permlane16_swap_b32_e32 v153, v151
	v_max_f32_e32 v150, v150, v152
	v_max_f32_e32 v151, v151, v153
	v_mov_b32_e32 v152, v150
	v_mov_b32_e32 v153, v151
	s_nop 0
	v_permlane32_swap_b32_e32 v152, v150
	v_permlane32_swap_b32_e32 v153, v151
	v_max_f32_e32 v150, v150, v152
	v_max_f32_e32 v151, v151, v153
	v_add_f32_e32 v110, 0x41000000, v144
	v_cmp_gt_f32_e32 vcc, v150, v110
	s_cbranch_vccz .Lna_l1_keep0
	v_max_f32_e32 v244, v144, v150
	v_sub_f32_e32 v110, v144, v244
	v_exp_f32_e32 v110, v110
	v_mov_b32_e32 v144, v244
	v_mul_f32_e32 v140, v140, v110
	v_pk_mul_f32 v[18:19], v[18:19], v[110:111] op_sel_hi:[1,0]
	v_pk_mul_f32 v[20:21], v[20:21], v[110:111] op_sel_hi:[1,0]
	v_pk_mul_f32 v[22:23], v[22:23], v[110:111] op_sel_hi:[1,0]
	v_pk_mul_f32 v[24:25], v[24:25], v[110:111] op_sel_hi:[1,0]
	v_pk_mul_f32 v[10:11], v[10:11], v[110:111] op_sel_hi:[1,0]
	v_pk_mul_f32 v[12:13], v[12:13], v[110:111] op_sel_hi:[1,0]
	v_pk_mul_f32 v[2:3], v[2:3], v[110:111] op_sel_hi:[1,0]
	v_pk_mul_f32 v[4:5], v[4:5], v[110:111] op_sel_hi:[1,0]

.Lna_l1_keep1:
	s_waitcnt lgkmcnt(6)
	ds_read_b64_tr_b16 v[180:181], v160 offset:23040
	ds_read_b64_tr_b16 v[182:183], v160 offset:25344
	ds_read_b64_tr_b16 v[184:185], v160 offset:23072
	ds_read_b64_tr_b16 v[186:187], v160 offset:25376
	ds_read_b64_tr_b16 v[154:155], v160 offset:23104
	ds_read_b64_tr_b16 v[156:157], v160 offset:25408
	ds_read_b64_tr_b16 v[200:201], v160 offset:23136
	ds_read_b64_tr_b16 v[202:203], v160 offset:25440
	v_sub_f32_e32 v70, v70, v144
	v_sub_f32_e32 v71, v71, v144
	v_exp_f32_e32 v70, v70
	v_sub_f32_e32 v72, v72, v144
	v_exp_f32_e32 v71, v71
	v_sub_f32_e32 v73, v73, v144
	v_exp_f32_e32 v72, v72
	v_exp_f32_e32 v73, v73
	v_sub_f32_e32 v78, v78, v144
	v_sub_f32_e32 v79, v79, v144
	v_exp_f32_e32 v78, v78
	v_sub_f32_e32 v80, v80, v144
	v_exp_f32_e32 v79, v79
	v_sub_f32_e32 v81, v81, v144
	v_exp_f32_e32 v80, v80
	v_exp_f32_e32 v81, v81
	v_add_f32_e32 v246, 0, v70
	v_add_f32_e32 v246, v71, v246
	v_add_f32_e32 v246, v72, v246
	v_add_f32_e32 v246, v73, v246
	v_cvt_pk_bf16_f32 v66, v70, v71
	v_cvt_pk_bf16_f32 v67, v72, v73
	v_add_f32_e32 v246, v78, v246
	v_add_f32_e32 v246, v79, v246
	v_add_f32_e32 v246, v80, v246
	v_add_f32_e32 v246, v81, v246
	v_cvt_pk_bf16_f32 v68, v78, v79
	v_cvt_pk_bf16_f32 v69, v80, v81
	v_add_f32_e32 v140, v140, v246
	s_nop 0
	v_mfma_f32_16x16x32_bf16 v[18:21], v[164:167], v[66:69], v[18:21]
	v_sub_f32_e32 v84, v84, v142
	v_sub_f32_e32 v85, v85, v142
	v_exp_f32_e32 v84, v84
	v_sub_f32_e32 v86, v86, v142
	v_exp_f32_e32 v85, v85
	v_sub_f32_e32 v87, v87, v142
	v_exp_f32_e32 v86, v86
	v_exp_f32_e32 v87, v87
	s_waitcnt lgkmcnt(12)
	v_mfma_f32_16x16x32_bf16 v[22:25], v[168:171], v[66:69], v[22:25]
	v_sub_f32_e32 v106, v106, v142
	v_sub_f32_e32 v107, v107, v142
	v_exp_f32_e32 v106, v106
	v_sub_f32_e32 v108, v108, v142
	v_exp_f32_e32 v107, v107
	v_sub_f32_e32 v109, v109, v142
	v_exp_f32_e32 v108, v108
	v_exp_f32_e32 v109, v109
	s_waitcnt lgkmcnt(10)
	v_mfma_f32_16x16x32_bf16 v[10:13], v[172:175], v[66:69], v[10:13]
	v_add_f32_e32 v247, 0, v84
	v_add_f32_e32 v247, v85, v247
	v_add_f32_e32 v247, v86, v247
	v_add_f32_e32 v247, v87, v247
	v_cvt_pk_bf16_f32 v74, v84, v85
	v_cvt_pk_bf16_f32 v75, v86, v87
	v_add_f32_e32 v247, v106, v247
	v_add_f32_e32 v247, v107, v247
	s_waitcnt lgkmcnt(8)
	v_mfma_f32_16x16x32_bf16 v[2:5], v[176:179], v[66:69], v[2:5]
	v_add_f32_e32 v247, v108, v247
	v_add_f32_e32 v247, v109, v247
	v_cvt_pk_bf16_f32 v76, v106, v107
	v_cvt_pk_bf16_f32 v77, v108, v109
	v_add_f32_e32 v137, v137, v247
	s_waitcnt lgkmcnt(6)
	v_mfma_f32_16x16x32_bf16 v[30:33], v[180:183], v[74:77], v[30:33]
	s_waitcnt lgkmcnt(4)
	v_mfma_f32_16x16x32_bf16 v[26:29], v[184:187], v[74:77], v[26:29]
	s_waitcnt lgkmcnt(2)
	v_mfma_f32_16x16x32_bf16 v[14:17], v[154:157], v[74:77], v[14:17]
	s_waitcnt lgkmcnt(0)
	v_mfma_f32_16x16x32_bf16 v[6:9], v[200:203], v[74:77], v[6:9]
	s_branch .LBB0_337
